# attention: V tile in LDS with 160-B rows and permuted keys so each PV fragment is one ds_read_b128 (16 LDS reads per tile fewer)
# speedup vs baseline: 1.0173x; 1.0010x over previous
; __device__ __forceinline__ void attn_phase(const Params& P, LAS unsigned char* lds, int tid, int wid, int lane) {
;     const int fr = lane & 15, fq = lane >> 4;
;     const bf16* PQ = (const bf16*)(P.ws + OFF_PQ); const bf16* PK = (const bf16*)(P.ws + OFF_PK); const bf16* Vt = (const bf16*)(P.ws + OFF_VT); bf16* CAT = (bf16*)(P.ws + OFF_RA);
;     float lam; { const float* lv = P.in[I_LAMV]; float a = lv[lane] * lv[64 + lane], c = lv[128 + lane] * lv[192 + lane]; a = wave_sum(a); c = wave_sum(c); lam = __expf(a) - __expf(c) + 0.2f; }
;     constexpr int KSTR = 272, VSTR = 144, KBUF = 64 * KSTR, VBUF = 128 * VSTR, VOFF = 2 * KBUF;
;     const int kr = tid >> 3, kseg = tid & 7, vr = tid >> 2, vseg = tid & 3;
;     const int vcu_ = (gridDim.x % 8 == 0) ? ((int)blockIdx.x % 8) * ((int)gridDim.x / 8) + (int)blockIdx.x / 8 : (int)blockIdx.x;
;     for (int it = vcu_; it < 512; it += gridDim.x) {
;         const int i2 = it & 255, hi = it >> 8, bh = i2 >> 3, cpl = i2 & 7, cp = hi ? 15 - cpl : cpl, b = bh >> 2, hh = bh & 3;
;         const int c = 2 * cp + (wid >> 2), qframe = 128 * cp + 16 * wid + fr, qpos = qframe + NMETA, nt = 2 * cp + 3;
;         const float slope2 = 1.44269504f * __builtin_amdgcn_exp2f(-2.0f * (float)(hh + 1));
.LBB0_613:
	s_cmp_gt_i32 s88, 6
	s_cselect_b64 s[0:1], -1, 0
	s_cmp_lt_i32 s89, 7
	s_cselect_b64 s[2:3], -1, 0
	s_or_b64 s[0:1], s[0:1], s[2:3]
	s_and_b64 vcc, exec, s[0:1]
	s_cbranch_vccnz .LBB0_739
	v_lshlrev_b32_e32 v0, 2, v208
	s_waitcnt lgkmcnt(0)
	global_load_dword v1, v0, s[72:73]
	global_load_dword v2, v0, s[72:73] offset:256
	global_load_dword v3, v0, s[72:73] offset:512
	global_load_dword v4, v0, s[72:73] offset:768
	v_mbcnt_lo_u32_b32 v0, -1, 0
	v_mbcnt_hi_u32_b32 v0, -1, v0
	v_and_b32_e32 v5, 64, v0
	v_xor_b32_e32 v6, 1, v0
	v_add_u32_e32 v5, 64, v5
	v_cmp_lt_i32_e32 vcc, v6, v5
	v_xor_b32_e32 v7, 2, v0
	v_xor_b32_e32 v8, 4, v0
	v_cndmask_b32_e32 v6, v0, v6, vcc
	v_lshlrev_b32_e32 v6, 2, v6
	v_cmp_lt_i32_e32 vcc, v7, v5
	v_xor_b32_e32 v9, 8, v0
	v_xor_b32_e32 v10, 16, v0
	v_cndmask_b32_e32 v7, v0, v7, vcc
	v_lshlrev_b32_e32 v7, 2, v7
	v_cmp_lt_i32_e32 vcc, v8, v5
	s_ashr_i32 s2, s33, 31
	s_lshr_b32 s2, s2, 29
	v_cndmask_b32_e32 v8, v0, v8, vcc
	v_cmp_lt_i32_e32 vcc, v9, v5
	v_xor_b32_e32 v11, 32, v0
	s_add_i32 s2, s33, s2
	s_and_b32 s3, s2, -8
	s_ashr_i32 s1, s96, 3
	s_sub_i32 s3, s33, s3
	s_ashr_i32 s2, s2, 3
	s_mul_i32 s1, s1, s3
	s_and_b32 s0, s96, 7
	s_add_i32 s1, s1, s2
	s_cmp_eq_u32 s0, 0
	s_cselect_b32 s17, s1, s33
	s_cmpk_gt_i32 s17, 0x1ff
	s_mov_b32 s7, 0
	s_waitcnt vmcnt(0)
	v_mul_f32_e32 v12, v1, v2
	ds_bpermute_b32 v12, v6, v12
	v_mul_f32_e32 v13, v3, v4
	ds_bpermute_b32 v6, v6, v13
	s_waitcnt lgkmcnt(1)
	v_fmac_f32_e32 v12, v1, v2
	ds_bpermute_b32 v1, v7, v12
	s_waitcnt lgkmcnt(1)
	v_fmac_f32_e32 v6, v3, v4
	ds_bpermute_b32 v2, v7, v6
	v_lshlrev_b32_e32 v4, 2, v8
	v_cndmask_b32_e32 v3, v0, v9, vcc
	s_waitcnt lgkmcnt(1)
	v_add_f32_e32 v1, v12, v1
	v_lshlrev_b32_e32 v3, 2, v3
	s_waitcnt lgkmcnt(0)
	v_add_f32_e32 v2, v6, v2
	ds_bpermute_b32 v6, v4, v1
	ds_bpermute_b32 v4, v4, v2
	v_cmp_lt_i32_e32 vcc, v10, v5
	s_waitcnt lgkmcnt(1)
	v_add_f32_e32 v1, v1, v6
	s_waitcnt lgkmcnt(0)
	v_add_f32_e32 v2, v2, v4
	ds_bpermute_b32 v4, v3, v1
	ds_bpermute_b32 v3, v3, v2
	v_cndmask_b32_e32 v7, v0, v10, vcc
	v_lshlrev_b32_e32 v211, 2, v7
	v_cmp_lt_i32_e32 vcc, v11, v5
	s_waitcnt lgkmcnt(1)
	v_add_f32_e32 v1, v1, v4
	s_waitcnt lgkmcnt(0)
	v_add_f32_e32 v2, v2, v3
	ds_bpermute_b32 v3, v211, v1
	ds_bpermute_b32 v4, v211, v2
	v_cndmask_b32_e32 v0, v0, v11, vcc
	v_lshlrev_b32_e32 v238, 2, v0
	s_waitcnt lgkmcnt(1)
	v_add_f32_e32 v0, v1, v3
	s_waitcnt lgkmcnt(0)
	v_add_f32_e32 v1, v2, v4
	ds_bpermute_b32 v2, v238, v0
	ds_bpermute_b32 v3, v238, v1
	s_cbranch_scc1 .LBB0_685
	s_waitcnt lgkmcnt(1)
	v_add_f32_e32 v0, v0, v2
	s_add_u32 s8, s86, 0x4d00000
	s_waitcnt lgkmcnt(0)
	v_add_f32_e32 v1, v1, v3
	v_mul_f32_e32 v0, 0x3fb8aa3b, v0
	s_addc_u32 s9, s87, 0
	v_exp_f32_e32 v2, v0
	v_mul_f32_e32 v0, 0x3fb8aa3b, v1
	s_add_u32 s10, s86, 0x5d40000
	s_movk_i32 s0, 0x80
	v_exp_f32_e32 v3, v0
	s_addc_u32 s11, s87, 0
	v_lshrrev_b32_e32 v239, 3, v209
	v_and_b32_e32 v10, 3, v209
	v_mov_b32_e32 v5, 0
	v_cmp_gt_u32_e64 s[2:3], s0, v209
	s_movk_i32 s0, 0x110
	v_and_b32_e32 v11, 48, v209
	v_and_b32_e32 v7, 15, v209
	v_lshrrev_b32_e32 v9, 4, v208
	s_add_u32 s12, s86, 0x2c00000
	v_lshrrev_b32_e32 v240, 2, v209
	v_mad_u32_u24 v16, v239, s0, 0
	s_movk_i32 s0, 0x90
	v_lshlrev_b32_e32 v10, 4, v10
	v_add_u32_e32 v18, 0, v11
	v_mov_b32_e32 v11, v5
	s_addc_u32 s13, s87, 0
	v_and_b32_e32 v4, 7, v209
	s_lshr_b32 s28, s92, 8
	v_lshl_or_b32 v241, s91, 4, v7
	v_lshlrev_b32_e32 v6, 3, v9
	v_mad_u32_u24 v17, v240, s0, 0
	v_mul_u32_u24_e32 v19, 0x110, v7
	v_mul_u32_u24_e32 v7, 0x90, v7
	v_lshl_add_u64 v[12:13], s[86:87], 0, v[10:11]
	s_mov_b64 s[0:1], 0xb700000
	v_and_b32_e32 v0, 48, v208
	v_mov_b32_e32 v1, v5
	v_lshlrev_b32_e32 v8, 3, v4
	v_lshlrev_b32_e32 v4, 4, v4
	v_lshlrev_b32_e32 v210, 2, v9
	v_add3_u32 v245, 0, v6, v7
	v_lshl_add_u64 v[214:215], v[12:13], 0, s[0:1]
	v_lshlrev_b32_e32 v14, 5, v9
	v_mov_b32_e32 v15, v5
	v_lshl_add_u64 v[218:219], s[74:75], 0, v[0:1]
	v_sub_f32_e32 v0, v2, v3
	s_lshl_b32 s29, s28, 6
	s_mov_b64 s[0:1], 0xb700140
	s_mov_b32 s14, -2.0
	v_or_b32_e32 v242, 0x4000, v239
	v_add_u32_e32 v243, -16, v239
	v_add_u32_e32 v244, 48, v239
	v_lshl_add_u64 v[212:213], s[10:11], 0, v[4:5]
	v_add_u32_e32 v246, 0xd000, v245
	v_add_u32_e32 v247, 0xd040, v245
	v_lshl_add_u64 v[216:217], s[68:69], 0, v[14:15]
	v_add_f32_e32 v248, 0x3e4ccccd, v0
	v_sub_u32_e32 v249, v241, v210
	v_lshl_add_u64 v[220:221], v[12:13], 0, s[0:1]
	s_sub_i32 s30, s29, 64
	v_lshlrev_b32_e32 v222, 1, v6
	v_mov_b32_e32 v250, 0x358637bd
	v_lshlrev_b32_e32 v224, 1, v8
	s_mov_b32 s15, 0xc0400000
	s_mov_b32 s16, 0xc1400000
	s_mov_b64 s[18:19], 0x100
	v_lshlrev_b32_e32 v226, 1, v210
	v_add_u32_e32 v251, v16, v4
	v_add_u32_e32 v252, v17, v10
	v_add_u32_e32 v253, v18, v19
	v_and_b32_e32 v0, 3, v209
	v_and_b32_e32 v1, 1, v0
	v_lshlrev_b32_e32 v1, 5, v1
	v_lshrrev_b32_e32 v0, 1, v0
	v_lshl_or_b32 v1, v0, 3, v1
	s_movk_i32 s0, 0xa0
	v_mad_u32_u24 v252, v240, s0, v1
	v_add_u32_e32 v252, 0x8800, v252
	s_branch .LBB0_617

; __device__ __forceinline__ float bf2f(unsigned h) { return __uint_as_float(h << 16); }
; __device__ __forceinline__ void attn_phase(const Params& P, LAS unsigned char* lds, int tid, int wid, int lane) {
;     ...
;     for (int it = vcu_; it < 512; it += gridDim.x) {
;         const int i2 = it & 255, hi = it >> 8, bh = i2 >> 3, cpl = i2 & 7, cp = hi ? 15 - cpl : cpl, b = bh >> 2, hh = bh & 3;
;         const int c = 2 * cp + (wid >> 2), qframe = 128 * cp + 16 * wid + fr, qpos = qframe + NMETA, nt = 2 * cp + 3;
;         const float slope2 = 1.44269504f * __builtin_amdgcn_exp2f(-2.0f * (float)(hh + 1));
;         const bf16* qrow = PQ + (size_t)(b * SEQ + qframe) * 512 + hh * 128;
;         bf16x8 qf[2][2];
; #pragma unroll
;         for (int cm = 0; cm < 2; ++cm)
; #pragma unroll
;             for (int ks = 0; ks < 2; ++ks) qf[cm][ks] = *(const bf16x8*)(qrow + 64 * cm + 32 * ks + 8 * fq);
; #pragma unroll
;         for (int cm = 0; cm < 2; ++cm) {
;             float x[2][8]; float ss = 0.f;
; #pragma unroll
;             for (int ks = 0; ks < 2; ++ks) { const u32x4 raw = __builtin_bit_cast(u32x4, qf[cm][ks]);
; #pragma unroll
;                 for (int i = 0; i < 4; ++i) { x[ks][2 * i] = bf2f(raw[i] & 0xffffu); x[ks][2 * i + 1] = bf2f(raw[i] >> 16); ss += x[ks][2 * i] * x[ks][2 * i] + x[ks][2 * i + 1] * x[ks][2 * i + 1]; } }
;             ss += __shfl_xor(ss, 16); ss += __shfl_xor(ss, 32);
;             const float rq_ = QSCALE * __builtin_amdgcn_rsqf(ss * (1.0f / 64.0f) + 1e-6f);
; #pragma unroll
;             for (int ks = 0; ks < 2; ++ks) { const f32x4 g0 = *(const f32x4*)(P.in[I_QN] + 32 * ks + 8 * fq), g1 = *(const f32x4*)(P.in[I_QN] + 32 * ks + 8 * fq + 4);
;                 const u32x4 w = (u32x4){pk2(x[ks][0] * rq_ * g0[0], x[ks][1] * rq_ * g0[1]), pk2(x[ks][2] * rq_ * g0[2], x[ks][3] * rq_ * g0[3]), pk2(x[ks][4] * rq_ * g1[0], x[ks][5] * rq_ * g1[1]), pk2(x[ks][6] * rq_ * g1[2], x[ks][7] * rq_ * g1[3])};
;                 qf[cm][ks] = __builtin_bit_cast(bf16x8, w); }
;         }
;         f32x4 O[2][8];
; #pragma unroll
;         for (int cm = 0; cm < 2; ++cm)
; #pragma unroll
;             for (int dt = 0; dt < 8; ++dt) O[cm][dt] = (f32x4){0.f, 0.f, 0.f, 0.f};
;         float l0 = 0.f, l1 = 0.f;
;         u32x4 ak0, ak1, av0, av1;
;     ...
;         __syncthreads();
;         ATT_LOADK(a, 0); ATT_LOADV(a, 0); ATT_WRITEK(a, 0); ATT_WRITEV(a, 0);
.LBB0_617:
	s_and_b32 s0, s17, 7
	s_xor_b32 s1, s0, 15
	s_cmpk_lt_u32 s17, 0x100
	s_cselect_b32 s1, s0, s1
	s_lshl_b32 s31, s1, 7
	s_lshl_b32 s0, s17, 6
	v_add_u32_e32 v103, s31, v241
	s_and_b32 s0, s0, 0x3800
	v_add_u32_e32 v228, s0, v103
	v_mov_b32_e32 v229, v5
	s_bfe_u32 s4, s17, 0x20003
	v_lshlrev_b64 v[0:1], 10, v[228:229]
	v_lshl_add_u64 v[0:1], s[8:9], 0, v[0:1]
	s_lshl_b32 s6, s4, 8
	v_lshl_add_u64 v[0:1], v[0:1], 0, s[6:7]
	v_mov_b32_e32 v223, v5
	v_lshl_add_u64 v[0:1], v[0:1], 0, v[222:223]
	global_load_dwordx4 v[30:33], v[0:1], off offset:64
	global_load_dwordx4 v[26:29], v[0:1], off
	global_load_dwordx4 v[22:25], v[0:1], off offset:192
	global_load_dwordx4 v[18:21], v[0:1], off offset:128
	global_load_dwordx4 v[10:13], v[216:217], off offset:16
	global_load_dwordx4 v[14:17], v[216:217], off
	s_nop 0
	global_load_dwordx4 v[0:3], v[216:217], off offset:144
	global_load_dwordx4 v[6:9], v[216:217], off offset:128
	s_not_b32 s20, s4
	s_lshl_b32 s20, s20, 1
	v_cvt_f32_i32_e32 v38, s20
	s_lshl_b32 s5, s17, 4
	s_and_b32 s5, s5, 0xf80
	v_add_u32_e32 v4, s0, v243
	v_exp_f32_e32 v116, v38
	v_add_u32_e32 v35, s5, v240
	v_cndmask_b32_e64 v34, v4, v242, s[2:3]
	v_mul_u32_u24_e32 v4, 0x840, v35
	v_ashrrev_i32_e32 v35, 31, v34
	v_lshlrev_b64 v[34:35], 10, v[34:35]
	v_lshlrev_b32_e32 v4, 1, v4
	v_lshl_add_u64 v[34:35], s[10:11], 0, v[34:35]
	v_mov_b32_e32 v225, v5
	v_lshl_add_u64 v[36:37], v[214:215], 0, v[4:5]
	v_lshl_add_u64 v[34:35], v[34:35], 0, s[6:7]
	s_barrier
	v_lshl_add_u64 v[34:35], v[34:35], 0, v[224:225]
	s_lshl_b32 s35, s1, 1
	s_add_i32 s40, s29, s31
	v_lshl_add_u64 v[232:233], v[220:221], 0, v[4:5]
	v_mov_b32_e32 v4, v5
	s_lshl_b32 s34, s4, 7
	s_add_i32 s36, s35, 3
	s_add_i32 s37, s35, s28
	v_lshl_add_u64 v[230:231], v[212:213], 0, s[6:7]
	s_add_i32 s41, s40, 64
	s_add_i32 s42, s30, s31
	s_mov_b32 s43, 0
	s_mov_b32 s45, 2
	v_mov_b32_e32 v223, v249
	v_mov_b64_e32 v[234:235], v[4:5]
	s_waitcnt vmcnt(7)
	v_and_b32_e32 v39, 0xffff0000, v33
	v_and_b32_e32 v41, 0xffff0000, v32
	v_and_b32_e32 v43, 0xffff0000, v31
	v_and_b32_e32 v45, 0xffff0000, v30
	s_waitcnt vmcnt(6)
	v_and_b32_e32 v47, 0xffff0000, v29
	v_and_b32_e32 v81, 0xffff0000, v28
	v_lshlrev_b32_e32 v82, 16, v27
	v_and_b32_e32 v83, 0xffff0000, v27
	v_lshlrev_b32_e32 v92, 16, v26
	v_and_b32_e32 v93, 0xffff0000, v26
	v_lshlrev_b32_e32 v38, 16, v33
	v_lshlrev_b32_e32 v40, 16, v32
	v_lshlrev_b32_e32 v42, 16, v31
	v_lshlrev_b32_e32 v44, 16, v30
	v_lshlrev_b32_e32 v46, 16, v29
	v_lshlrev_b32_e32 v80, 16, v28
	v_mov_b32_e32 v28, v39
	v_mov_b32_e32 v29, v41
	v_mov_b32_e32 v32, v43
	v_mov_b32_e32 v33, v45
	v_mov_b32_e32 v86, v47
	v_mov_b32_e32 v87, v81
	v_pk_mul_f32 v[88:89], v[82:83], v[82:83]
	v_pk_mul_f32 v[90:91], v[92:93], v[92:93]
	v_mov_b32_e32 v26, v38
	v_mov_b32_e32 v27, v40
	v_mov_b32_e32 v30, v42
	v_mov_b32_e32 v31, v44
	v_mov_b32_e32 v84, v46
	v_mov_b32_e32 v85, v80
	v_pk_mul_f32 v[28:29], v[28:29], v[28:29]
	v_pk_mul_f32 v[32:33], v[32:33], v[32:33]
	v_pk_mul_f32 v[86:87], v[86:87], v[86:87]
	v_add_f32_e32 v88, v88, v89
	v_add_f32_e32 v89, v90, v91
	v_pk_fma_f32 v[26:27], v[26:27], v[26:27], v[28:29]
	v_pk_fma_f32 v[28:29], v[30:31], v[30:31], v[32:33]
	v_pk_fma_f32 v[30:31], v[84:85], v[84:85], v[86:87]
	v_add_f32_e32 v32, v89, v88
	v_add_f32_e32 v31, v31, v32
	v_add_f32_e32 v30, v30, v31
	v_add_f32_e32 v29, v29, v30
	v_add_f32_e32 v28, v28, v29
	v_add_f32_e32 v27, v27, v28
	v_add_f32_e32 v94, v26, v27
	ds_bpermute_b32 v95, v211, v94
	global_load_dwordx4 v[84:87], v[36:37], off
	global_load_dwordx4 v[88:91], v[36:37], off offset:64
	global_load_dwordx4 v[26:29], v[34:35], off
	global_load_dwordx4 v[30:33], v[34:35], off offset:128
	s_waitcnt vmcnt(9)
	v_lshlrev_b32_e32 v36, 16, v24
	v_and_b32_e32 v37, 0xffff0000, v24
	v_and_b32_e32 v35, 0xffff0000, v25
	s_waitcnt lgkmcnt(0)
	v_add_f32_e32 v94, v94, v95
	ds_bpermute_b32 v95, v238, v94
	v_lshlrev_b32_e32 v34, 16, v25
	v_mov_b32_e32 v100, v35
	v_mov_b32_e32 v101, v37
	v_mov_b32_e32 v25, v36
	s_waitcnt lgkmcnt(0)
	v_add_f32_e32 v24, v94, v95
	v_fmamk_f32 v24, v24, 0x3c800000, v250
	v_rsq_f32_e32 v94, v24
	v_mov_b32_e32 v24, v34
	s_waitcnt vmcnt(8)
	v_and_b32_e32 v109, 0xffff0000, v21
	v_and_b32_e32 v111, 0xffff0000, v20
	v_mul_f32_e32 v102, 0x3e38aa3b, v94
	v_pk_mul_f32 v[82:83], v[102:103], v[82:83] op_sel_hi:[0,1]
	v_pk_mul_f32 v[46:47], v[102:103], v[46:47] op_sel_hi:[0,1]
	v_pk_mul_f32 v[80:81], v[102:103], v[80:81] op_sel_hi:[0,1]
	s_waitcnt vmcnt(6)
	v_pk_mul_f32 v[82:83], v[16:17], v[82:83]
	v_pk_mul_f32 v[46:47], v[12:13], v[46:47]
	v_pk_mul_f32 v[94:95], v[10:11], v[80:81]
	v_cvt_pk_bf16_f32 v81, v82, v83
	v_cvt_pk_bf16_f32 v83, v46, v47
	v_or_b32_e32 v46, s0, v244
	v_lshlrev_b32_e32 v46, 10, v46
	v_mov_b32_e32 v47, v5
	v_lshl_add_u64 v[46:47], s[10:11], 0, v[46:47]
	v_pk_mul_f32 v[92:93], v[102:103], v[92:93] op_sel_hi:[0,1]
	v_lshl_add_u64 v[46:47], v[46:47], 0, s[6:7]
	v_pk_mul_f32 v[92:93], v[14:15], v[92:93]
	v_lshl_add_u64 v[46:47], v[46:47], 0, v[224:225]
	v_cvt_pk_bf16_f32 v80, v92, v93
	v_cvt_pk_bf16_f32 v82, v94, v95
	global_load_dwordx4 v[92:95], v[46:47], off
	global_load_dwordx4 v[96:99], v[46:47], off offset:128
	v_pk_mul_f32 v[46:47], v[100:101], v[100:101]
	v_and_b32_e32 v101, 0xffff0000, v22
	v_pk_fma_f32 v[24:25], v[24:25], v[24:25], v[46:47]
	v_and_b32_e32 v47, 0xffff0000, v23
	v_lshlrev_b32_e32 v46, 16, v23
	v_lshlrev_b32_e32 v100, 16, v22
	v_mov_b32_e32 v104, v47
	v_mov_b32_e32 v105, v101
	v_mov_b32_e32 v22, v46
	v_mov_b32_e32 v23, v100
	v_pk_mul_f32 v[104:105], v[104:105], v[104:105]
	v_lshlrev_b32_e32 v108, 16, v21
	v_pk_fma_f32 v[22:23], v[22:23], v[22:23], v[104:105]
	v_lshlrev_b32_e32 v110, 16, v20
	v_mov_b32_e32 v104, v109
	v_mov_b32_e32 v105, v111
	v_mov_b32_e32 v20, v108
	v_mov_b32_e32 v21, v110
	v_pk_mul_f32 v[104:105], v[104:105], v[104:105]
	v_lshlrev_b32_e32 v114, 16, v19
	v_and_b32_e32 v115, 0xffff0000, v19
	v_lshlrev_b32_e32 v112, 16, v18
	v_and_b32_e32 v113, 0xffff0000, v18
	v_pk_fma_f32 v[20:21], v[20:21], v[20:21], v[104:105]
	v_pk_mul_f32 v[104:105], v[114:115], v[114:115]
	v_pk_mul_f32 v[18:19], v[112:113], v[112:113]
	v_add_f32_e32 v104, v104, v105
	v_add_f32_e32 v18, v18, v19
	v_add_f32_e32 v18, v18, v104
	v_add_f32_e32 v18, v21, v18
	v_add_f32_e32 v18, v20, v18
	v_add_f32_e32 v18, v23, v18
	v_add_f32_e32 v18, v22, v18
	v_add_f32_e32 v18, v25, v18
	v_add_f32_e32 v20, v24, v18
	ds_bpermute_b32 v21, v211, v20
	v_pk_mul_f32 v[44:45], v[102:103], v[44:45] op_sel_hi:[0,1]
	s_waitcnt vmcnt(6)
; #define LAS __attribute__((address_space(3)))
; #define ATT_LOADK(S, j) do { int pos_ = 64 * (j) + kr; pos_ = pos_ < LPOS ? pos_ : LPOS - 1; const bf16* kp_ = PK + (size_t)rowof(b, pos_) * 512 + hh * 128 + 8 * kseg; S##k0 = *(const u32x4*)kp_; S##k1 = *(const u32x4*)(kp_ + 64); } while (0)
; #define ATT_LOADV(S, j) do { const bf16* vp_ = Vt + ((size_t)bh * 128 + vr) * VT_LD + 64 * (j) + 8 * vseg; S##v0 = *(const u32x4*)vp_; S##v1 = *(const u32x4*)(vp_ + 32); } while (0)
; #define ATT_WRITEK(S, buf) do { LAS unsigned char* kb_ = lds + (buf) * KBUF + kr * KSTR + kseg * 16; *(LAS u32x4*)kb_ = S##k0; *(LAS u32x4*)(kb_ + 128) = S##k1; } while (0)
; #define ATT_WRITEV(S, buf) do { LAS unsigned char* vb_ = lds + VOFF + (buf) * VBUF + vr * VSTR + vseg * 16; *(LAS u32x4*)vb_ = S##v0; *(LAS u32x4*)(vb_ + 64) = S##v1; } while (0)
; __device__ __forceinline__ void att_qk(const LAS unsigned char* Kb, const bf16x8 (&qf)[2][2], int nst, int j, int qpos, float slope2, int fr, int fq, f32x4 (&sc)[2][4]) {
;     constexpr int KSTR = 272;
; #pragma unroll
;     for (int st = 0; st < 4; ++st) {
;         if (st < nst) {
;             const float d0 = (float)(qpos - (64 * j + 16 * st + 4 * fq));
;             f32x4 s0;
; #pragma unroll
;             for (int e = 0; e < 4; ++e) s0[e] = -slope2 * __builtin_fabsf(d0 - (float)e) - 12.0f;
;             f32x4 s1 = s0;
; #pragma unroll
;             for (int ks = 0; ks < 2; ++ks) {
;                 const bf16x8 k0 = *(const LAS bf16x8*)(Kb + (16 * st + fr) * KSTR + (32 * ks + 8 * fq) * 2);
;                 const bf16x8 k1 = *(const LAS bf16x8*)(Kb + (16 * st + fr) * KSTR + (64 + 32 * ks + 8 * fq) * 2);
;                 s0 = __builtin_amdgcn_mfma_f32_16x16x32_bf16(k0, qf[0][ks], s0, 0, 0, 0);
;                 s1 = __builtin_amdgcn_mfma_f32_16x16x32_bf16(k1, qf[1][ks], s1, 0, 0, 0);
;             }
;             sc[0][st] = s0; sc[1][st] = s1;
;         }
;     }
; __device__ __forceinline__ void attn_phase(const Params& P, LAS unsigned char* lds, int tid, int wid, int lane) {
;     ...
;         __syncthreads();
;         ATT_LOADK(a, 0); ATT_LOADV(a, 0); ATT_WRITEK(a, 0); ATT_WRITEV(a, 0);
;         if (nt > 1) { ATT_LOADK(a, 1); ATT_WRITEK(a, 1); }
;         __syncthreads();
;         f32x4 scA[2][4], scB[2][4];
;         att_qk(lds, qf, ATT_NST(0), 0, qpos, slope2, fr, fq, scA);
	v_pk_mul_f32 v[18:19], v[6:7], v[44:45]
	s_waitcnt vmcnt(3)
	ds_write_b128 v251, v[26:29]
	s_waitcnt vmcnt(2)
	ds_write_b128 v251, v[30:33] offset:128
	ds_write2_b64 v252, v[84:85], v[86:87] offset1:2
	ds_write2_b64 v252, v[88:89], v[90:91] offset0:8 offset1:10
	s_waitcnt vmcnt(1)
	ds_write_b128 v251, v[92:95] offset:17408
	s_waitcnt vmcnt(0)
	ds_write_b128 v251, v[96:99] offset:17536
	s_waitcnt lgkmcnt(6)
	v_add_f32_e32 v20, v20, v21
	ds_bpermute_b32 v21, v238, v20
	v_cvt_pk_bf16_f32 v104, v18, v19
	v_pk_mul_f32 v[18:19], v[102:103], v[42:43] op_sel_hi:[0,1]
	v_pk_mul_f32 v[18:19], v[8:9], v[18:19]
	v_sub_u32_e32 v28, v103, v210
	v_cvt_pk_bf16_f32 v105, v18, v19
	v_pk_mul_f32 v[18:19], v[102:103], v[40:41] op_sel_hi:[0,1]
	v_pk_mul_f32 v[18:19], v[0:1], v[18:19]
	s_waitcnt lgkmcnt(0)
	v_cvt_pk_bf16_f32 v106, v18, v19
	v_add_f32_e32 v18, v20, v21
	v_fmamk_f32 v18, v18, 0x3c800000, v250
	v_rsq_f32_e32 v20, v18
	v_pk_mul_f32 v[18:19], v[102:103], v[38:39] op_sel_hi:[0,1]
	v_pk_mul_f32 v[18:19], v[2:3], v[18:19]
	s_barrier
	v_mul_f32_e32 v38, 0x3e38aa3b, v20
	v_cvt_pk_bf16_f32 v107, v18, v19
	v_pk_mul_f32 v[18:19], v[38:39], v[112:113] op_sel_hi:[0,1]
	v_pk_mul_f32 v[14:15], v[14:15], v[18:19]
	s_nop 0
	v_cvt_pk_bf16_f32 v112, v14, v15
	v_pk_mul_f32 v[14:15], v[38:39], v[114:115] op_sel_hi:[0,1]
	v_pk_mul_f32 v[14:15], v[16:17], v[14:15]
	ds_read_b128 v[18:21], v253 offset:64
	v_cvt_pk_bf16_f32 v113, v14, v15
	v_pk_mul_f32 v[14:15], v[38:39], v[110:111] op_sel_hi:[0,1]
	v_pk_mul_f32 v[10:11], v[10:11], v[14:15]
	v_mul_f32_e32 v40, 0x3fb8aa3b, v116
	v_cvt_pk_bf16_f32 v114, v10, v11
	v_pk_mul_f32 v[10:11], v[38:39], v[108:109] op_sel_hi:[0,1]
	v_pk_mul_f32 v[10:11], v[12:13], v[10:11]
	v_pk_mul_f32 v[26:27], v[38:39], v[36:37] op_sel_hi:[0,1]
	v_cvt_pk_bf16_f32 v115, v10, v11
	v_pk_mul_f32 v[10:11], v[38:39], v[100:101] op_sel_hi:[0,1]
	v_pk_mul_f32 v[6:7], v[6:7], v[10:11]
	v_pk_mul_f32 v[0:1], v[0:1], v[26:27]
	v_cvt_pk_bf16_f32 v128, v6, v7
	v_pk_mul_f32 v[6:7], v[38:39], v[46:47] op_sel_hi:[0,1]
	v_pk_mul_f32 v[22:23], v[8:9], v[6:7]
	v_add_u32_e32 v6, 16, v28
	v_cvt_f32_u32_e32 v14, v6
	ds_read_b128 v[6:9], v253
	v_cvt_pk_bf16_f32 v129, v22, v23
	ds_read_b128 v[22:25], v253 offset:192
	v_add_f32_e32 v10, -1.0, v14
	v_and_b32_e32 v15, 0x7fffffff, v10
	ds_read_b128 v[10:13], v253 offset:128
	v_pk_add_f32 v[16:17], v[14:15], s[14:15] op_sel_hi:[0,1]
	v_and_b32_e32 v17, 0x7fffffff, v17
	v_and_b32_e32 v16, 0x7fffffff, v16
	v_pk_fma_f32 v[14:15], v[40:41], v[14:15], s[16:17] op_sel_hi:[0,1,0] neg_lo:[1,0,0] neg_hi:[1,0,0]
	v_pk_fma_f32 v[16:17], v[40:41], v[16:17], s[16:17] op_sel_hi:[0,1,0] neg_lo:[1,0,0] neg_hi:[1,0,0]
	v_cvt_pk_bf16_f32 v130, v0, v1
	v_pk_mul_f32 v[0:1], v[38:39], v[34:35] op_sel_hi:[0,1]
	s_waitcnt lgkmcnt(2)
	v_mfma_f32_16x16x32_bf16 v[6:9], v[6:9], v[80:83], v[14:17]
	v_mul_f32_e64 v0, v2, v0
	v_mul_f32_e64 v1, v3, v1
	v_mov_b32_e32 v102, v5
	v_cvt_pk_bf16_f32 v131, v0, v1
	s_waitcnt lgkmcnt(0)
	v_mfma_f32_16x16x32_bf16 v[10:13], v[10:13], v[112:115], v[14:17]
	ds_read_b128 v[0:3], v253 offset:4352
	v_mov_b32_e32 v103, v5
	v_readfirstlane_b32 s20, v40
	v_mfma_f32_16x16x32_bf16 v[152:155], v[18:21], v[104:107], v[6:9]
	v_mov_b32_e32 v100, v5
	v_mov_b32_e32 v101, v5
	v_mov_b64_e32 v[118:119], v[102:103]
	v_cvt_f32_i32_e32 v6, v28
	v_mfma_f32_16x16x32_bf16 v[156:159], v[22:25], v[128:131], v[10:13]
	v_mov_b64_e32 v[126:127], v[102:103]
	v_mov_b64_e32 v[138:139], v[102:103]
	v_add_f32_e32 v7, -1.0, v6
	ds_read_b128 v[10:13], v253 offset:4416
	v_pk_add_f32 v[8:9], v[6:7], s[14:15] op_sel_hi:[0,1]
	v_and_b32_e32 v9, 0x7fffffff, v9
	v_and_b32_e32 v8, 0x7fffffff, v8
	v_and_b32_e32 v6, 0x7fffffff, v6
	v_and_b32_e32 v7, 0x7fffffff, v7
	v_pk_fma_f32 v[6:7], v[40:41], v[6:7], s[16:17] op_sel_hi:[0,1,0] neg_lo:[1,0,0] neg_hi:[1,0,0]
	v_pk_fma_f32 v[8:9], v[40:41], v[8:9], s[16:17] op_sel_hi:[0,1,0] neg_lo:[1,0,0] neg_hi:[1,0,0]
	ds_read_b128 v[14:17], v253 offset:4480
	ds_read_b128 v[18:21], v253 offset:4544
	s_waitcnt lgkmcnt(3)
	v_mfma_f32_16x16x32_bf16 v[0:3], v[0:3], v[80:83], v[6:9]
	v_mov_b64_e32 v[146:147], v[102:103]
	v_mov_b64_e32 v[162:163], v[102:103]
	v_mov_b64_e32 v[178:179], v[102:103]
	s_waitcnt lgkmcnt(2)
	v_mfma_f32_16x16x32_bf16 v[168:171], v[10:13], v[104:107], v[0:3]
	v_mov_b64_e32 v[190:191], v[102:103]
	v_mov_b64_e32 v[110:111], v[102:103]
	v_mov_b64_e32 v[122:123], v[102:103]
	v_add_u32_e32 v0, -16, v28
	v_cvt_f32_i32_e32 v10, v0
	s_waitcnt lgkmcnt(1)
	v_mfma_f32_16x16x32_bf16 v[6:9], v[14:17], v[112:115], v[6:9]
	ds_read_b128 v[0:3], v253 offset:8704
	v_mov_b64_e32 v[134:135], v[102:103]
	v_add_f32_e32 v11, -1.0, v10
	s_waitcnt lgkmcnt(1)
	v_mfma_f32_16x16x32_bf16 v[172:175], v[18:21], v[128:131], v[6:9]
	v_mov_b64_e32 v[142:143], v[102:103]
	v_mov_b64_e32 v[150:151], v[102:103]
	v_mov_b64_e32 v[166:167], v[102:103]
	v_pk_add_f32 v[6:7], v[10:11], s[14:15] op_sel_hi:[0,1]
	v_and_b32_e32 v9, 0x7fffffff, v7
	v_and_b32_e32 v8, 0x7fffffff, v6
	v_and_b32_e32 v6, 0x7fffffff, v10
	v_and_b32_e32 v7, 0x7fffffff, v11
	ds_read_b128 v[10:13], v253 offset:8768
	v_pk_fma_f32 v[6:7], v[40:41], v[6:7], s[16:17] op_sel_hi:[0,1,0] neg_lo:[1,0,0] neg_hi:[1,0,0]
	v_pk_fma_f32 v[8:9], v[40:41], v[8:9], s[16:17] op_sel_hi:[0,1,0] neg_lo:[1,0,0] neg_hi:[1,0,0]
	ds_read_b128 v[14:17], v253 offset:8832
	ds_read_b128 v[18:21], v253 offset:8896
	s_waitcnt lgkmcnt(3)
; #define ATT_LOADK(S, j) do { int pos_ = 64 * (j) + kr; pos_ = pos_ < LPOS ? pos_ : LPOS - 1; const bf16* kp_ = PK + (size_t)rowof(b, pos_) * 512 + hh * 128 + 8 * kseg; S##k0 = *(const u32x4*)kp_; S##k1 = *(const u32x4*)(kp_ + 64); } while (0)
; #define ATT_LOADV(S, j) do { const bf16* vp_ = Vt + ((size_t)bh * 128 + vr) * VT_LD + 64 * (j) + 8 * vseg; S##v0 = *(const u32x4*)vp_; S##v1 = *(const u32x4*)(vp_ + 32); } while (0)
; #define ATT_WRITEK(S, buf) do { LAS unsigned char* kb_ = lds + (buf) * KBUF + kr * KSTR + kseg * 16; *(LAS u32x4*)kb_ = S##k0; *(LAS u32x4*)(kb_ + 128) = S##k1; } while (0)
; #define ATT_WRITEV(S, buf) do { LAS unsigned char* vb_ = lds + VOFF + (buf) * VBUF + vr * VSTR + vseg * 16; *(LAS u32x4*)vb_ = S##v0; *(LAS u32x4*)(vb_ + 64) = S##v1; } while (0)
; __device__ __forceinline__ void attn_phase(const Params& P, LAS unsigned char* lds, int tid, int wid, int lane) {
;     ...
;         f32x4 O[2][8];
; #pragma unroll
;         for (int cm = 0; cm < 2; ++cm)
; #pragma unroll
;             for (int dt = 0; dt < 8; ++dt) O[cm][dt] = (f32x4){0.f, 0.f, 0.f, 0.f};
;         float l0 = 0.f, l1 = 0.f;
;         u32x4 ak0, ak1, av0, av1;
;     ...
;         __syncthreads();
;         ATT_LOADK(a, 0); ATT_LOADV(a, 0); ATT_WRITEK(a, 0); ATT_WRITEV(a, 0);
;         if (nt > 1) { ATT_LOADK(a, 1); ATT_WRITEK(a, 1); }
;         __syncthreads();
;         f32x4 scA[2][4], scB[2][4];
;         att_qk(lds, qf, ATT_NST(0), 0, qpos, slope2, fr, fq, scA);
;         for (int j = 0; j < nt; j += 2) {
;             if (j + 1 < nt) { if (j + 2 < nt) ATT_LOADK(a, j + 2); ATT_LOADV(a, j + 1); }
	v_mfma_f32_16x16x32_bf16 v[0:3], v[0:3], v[80:83], v[6:9]
	v_mov_b64_e32 v[182:183], v[102:103]
	v_mov_b64_e32 v[186:187], v[102:103]
	s_mov_b32 s21, s20
	s_waitcnt lgkmcnt(2)
	v_mfma_f32_16x16x32_bf16 v[192:195], v[10:13], v[104:107], v[0:3]
	s_mov_b32 s38, s20
	s_mov_b32 s39, s20
	s_nop 0
	v_subrev_u32_e32 v0, 32, v28
	v_cvt_f32_i32_e32 v10, v0
	s_waitcnt lgkmcnt(1)
	v_mfma_f32_16x16x32_bf16 v[6:9], v[14:17], v[112:115], v[6:9]
	ds_read_b128 v[0:3], v253 offset:13056
	ds_read_b128 v[14:17], v253 offset:13120
	v_add_f32_e32 v11, -1.0, v10
	s_waitcnt lgkmcnt(2)
	v_mfma_f32_16x16x32_bf16 v[196:199], v[18:21], v[128:131], v[6:9]
	ds_read_b128 v[18:21], v253 offset:13248
	s_add_i32 s6, s0, -16
	v_mov_b64_e32 v[116:117], v[100:101]
	v_pk_add_f32 v[6:7], v[10:11], s[14:15] op_sel_hi:[0,1]
	v_and_b32_e32 v13, 0x7fffffff, v7
	v_and_b32_e32 v12, 0x7fffffff, v6
	ds_read_b128 v[6:9], v253 offset:13184
	v_and_b32_e32 v10, 0x7fffffff, v10
	v_and_b32_e32 v11, 0x7fffffff, v11
	v_pk_fma_f32 v[10:11], v[40:41], v[10:11], s[16:17] op_sel_hi:[0,1,0] neg_lo:[1,0,0] neg_hi:[1,0,0]
	v_pk_fma_f32 v[12:13], v[40:41], v[12:13], s[16:17] op_sel_hi:[0,1,0] neg_lo:[1,0,0] neg_hi:[1,0,0]
	v_mov_b64_e32 v[124:125], v[100:101]
	v_mov_b64_e32 v[136:137], v[100:101]
	s_waitcnt lgkmcnt(3)
	v_mfma_f32_16x16x32_bf16 v[0:3], v[0:3], v[80:83], v[10:13]
	v_mov_b64_e32 v[144:145], v[100:101]
	v_mov_b64_e32 v[160:161], v[100:101]
	v_mov_b64_e32 v[176:177], v[100:101]
	s_waitcnt lgkmcnt(0)
	v_mfma_f32_16x16x32_bf16 v[6:9], v[6:9], v[112:115], v[10:13]
	v_mov_b64_e32 v[188:189], v[100:101]
	v_mov_b64_e32 v[108:109], v[100:101]
	v_mov_b64_e32 v[120:121], v[100:101]
	v_mfma_f32_16x16x32_bf16 v[200:203], v[14:17], v[104:107], v[0:3]
	v_mov_b64_e32 v[132:133], v[100:101]
	v_mov_b64_e32 v[140:141], v[100:101]
	v_mov_b64_e32 v[148:149], v[100:101]
	v_mfma_f32_16x16x32_bf16 v[204:207], v[18:21], v[128:131], v[6:9]
	v_mov_b64_e32 v[164:165], v[100:101]
	v_mov_b64_e32 v[180:181], v[100:101]
	v_mov_b64_e32 v[184:185], v[100:101]
	s_branch .LBB0_619
.LBB0_619:
	s_add_i32 s0, s6, 16
	s_lshl_b32 s0, s0, 10
	s_lshl_b32 s1, s34, 1
	s_add_u32 s22, s10, s0
	s_addc_u32 s23, s11, 0
	s_add_u32 s22, s22, s1
	s_addc_u32 s23, s23, 0
	s_bfe_u32 s0, s17, 0x50003
	s_mul_i32 s0, s0, 0x84000
	s_add_u32 s24, s86, 0xb700000
	s_addc_u32 s25, s87, 0
	s_add_u32 s24, s24, s0
	s_addc_u32 s25, s25, 0
	s_mov_b32 s18, 0xc6ea6000
	s_xor_b32 s19, s20, 0x80000000
	s_movk_i32 s46, 0x1080
	s_mov_b32 s4, 0
	v_and_b32_e32 v46, 3, v209
	v_lshlrev_b32_e32 v46, 4, v46
	v_mad_u32_u24 v46, v240, s46, v46
	v_add_u32_e32 v47, s31, v249
	v_add_u32_e32 v47, 16, v47
	v_cvt_f32_i32_e32 v47, v47
	v_add_f32_e32 v47, 0xc2800000, v47
	v_mov_b32_e32 v236, 0
	v_mov_b32_e32 v237, 0
	v_and_b32_e32 v225, 15, v209
	v_mul_u32_u24_e32 v225, 0xa0, v225
	v_lshl_add_u32 v225, v210, 2, v225
	v_add_u32_e32 v225, 0x8800, v225
	v_add_u32_e32 v246, 0x5000, v225
	v_add_u32_e32 v247, 0x5000, v252
	s_mov_b32 s5, 1
	s_cmp_le_u32 s5, s37
	s_cselect_b32 s45, s16, s18
	s_add_i32 s0, s37, 1
	s_cmp_le_u32 s5, s0
	s_cselect_b32 s43, s16, s18
	v_mov_b32_e32 v4, s43
	v_fma_f32 v48, |v47|, s19, v4
	v_subrev_f32_e32 v49, 0x3f800000, v47
	v_fma_f32 v49, |v49|, s19, v4
	v_subrev_f32_e32 v50, 0x40000000, v47
	v_fma_f32 v50, |v50|, s19, v4
	v_subrev_f32_e32 v51, 0x40400000, v47
	v_fma_f32 v51, |v51|, s19, v4
	v_mov_b32_e32 v4, s45
	v_subrev_f32_e32 v52, 0x41800000, v47
	v_fma_f32 v52, |v52|, s19, v4
	v_subrev_f32_e32 v53, 0x41880000, v47
	v_fma_f32 v53, |v53|, s19, v4
	v_subrev_f32_e32 v54, 0x41900000, v47
	v_fma_f32 v54, |v54|, s19, v4
	v_subrev_f32_e32 v55, 0x41980000, v47
	v_fma_f32 v55, |v55|, s19, v4
	v_subrev_f32_e32 v56, 0x42000000, v47
	v_fma_f32 v56, |v56|, s19, v4
	v_subrev_f32_e32 v57, 0x42040000, v47
	v_fma_f32 v57, |v57|, s19, v4
	v_subrev_f32_e32 v58, 0x42080000, v47
	v_fma_f32 v58, |v58|, s19, v4
	v_subrev_f32_e32 v59, 0x420c0000, v47
	v_fma_f32 v59, |v59|, s19, v4
	v_subrev_f32_e32 v60, 0x42400000, v47
	v_fma_f32 v60, |v60|, s19, v4
	v_subrev_f32_e32 v61, 0x42440000, v47
	v_fma_f32 v61, |v61|, s19, v4
	v_subrev_f32_e32 v62, 0x42480000, v47
	v_fma_f32 v62, |v62|, s19, v4
	v_subrev_f32_e32 v63, 0x424c0000, v47
	v_fma_f32 v63, |v63|, s19, v4
	v_add_f32_e32 v47, 0xc2800000, v47
	s_sub_i32 s1, s36, 1
	s_add_i32 s0, s4, 2
	s_min_u32 s0, s0, s1
	s_add_i32 s5, s4, 1
	s_min_u32 s5, s5, s1
	s_lshl_b32 s0, s0, 6
	s_lshl_b32 s5, s5, 7
	v_add_u32_e32 v223, s0, v243
	v_min_u32_e32 v223, 0x7ff, v223
	v_lshl_add_u32 v223, v223, 10, v224
	s_add_u32 s26, s24, s5
	s_addc_u32 s27, s25, 0
	global_load_dwordx4 v[84:87], v223, s[22:23]
	global_load_dwordx4 v[88:91], v223, s[22:23] offset:128
	global_load_dwordx4 v[92:95], v46, s[26:27]
	global_load_dwordx4 v[96:99], v46, s[26:27] offset:64

; #define LAS __attribute__((address_space(3)))
; __device__ __forceinline__ void att_pv(const LAS unsigned char* Vb, int nst, const f32x4 (&sc)[2][4], f32x4 (&O)[2][8], float& l0, float& l1, int fr, int fq) {
;     constexpr int VSTR = 144;
;     if (nst <= 0) return;
;     unsigned pw[2][4][2];
; #pragma unroll
;     for (int st = 0; st < 4; ++st) {
;         if (st < nst) {
;             float p0[4], p1[4];
; #pragma unroll
;             for (int e = 0; e < 4; ++e) { p0[e] = __builtin_amdgcn_exp2f(sc[0][st][e]); p1[e] = __builtin_amdgcn_exp2f(sc[1][st][e]); l0 += p0[e]; l1 += p1[e]; }
;             pw[0][st][0] = pk2(p0[0], p0[1]); pw[0][st][1] = pk2(p0[2], p0[3]); pw[1][st][0] = pk2(p1[0], p1[1]); pw[1][st][1] = pk2(p1[2], p1[3]);
;         } else { pw[0][st][0] = 0u; pw[0][st][1] = 0u; pw[1][st][0] = 0u; pw[1][st][1] = 0u; }
;     }
; #pragma unroll
;     for (int ks2 = 0; ks2 < 2; ++ks2) {
;         if (ks2 == 0 || nst == 4) {
;             const u32x4 a0 = (u32x4){pw[0][2 * ks2][0], pw[0][2 * ks2][1], pw[0][2 * ks2 + 1][0], pw[0][2 * ks2 + 1][1]};
;             const u32x4 a1 = (u32x4){pw[1][2 * ks2][0], pw[1][2 * ks2][1], pw[1][2 * ks2 + 1][0], pw[1][2 * ks2 + 1][1]};
;             const bf16x8 pf0 = __builtin_bit_cast(bf16x8, a0), pf1 = __builtin_bit_cast(bf16x8, a1);
; #pragma unroll
;             for (int dt = 0; dt < 8; ++dt) {
;                 const LAS unsigned char* vp = Vb + (16 * dt + fr) * VSTR + (32 * ks2 + 4 * fq) * 2;
;                 const u32x2 va = *(const LAS u32x2*)vp, vb2 = *(const LAS u32x2*)(vp + 32);
;                 const bf16x8 vf = __builtin_bit_cast(bf16x8, (u32x4){va.x, va.y, vb2.x, vb2.y});
;                 O[0][dt] = __builtin_amdgcn_mfma_f32_16x16x32_bf16(vf, pf0, O[0][dt], 0, 0, 0);
;                 O[1][dt] = __builtin_amdgcn_mfma_f32_16x16x32_bf16(vf, pf1, O[1][dt], 0, 0, 0);
;             }
;         }
;     }
; __device__ __forceinline__ void attn_phase(const Params& P, LAS unsigned char* lds, int tid, int wid, int lane) {
;     ...
;             if (j + 1 < nt) { if (j + 2 < nt) ATT_LOADK(a, j + 2); ATT_LOADV(a, j + 1); }
;             if (j + 1 < nt) att_qk(lds + KBUF, qf, ATT_NST(j + 1), j + 1, qpos, slope2, fr, fq, scB);
;             att_pv(lds + VOFF, ATT_NST(j), scA, O, l0, l1, fr, fq);
;             if (j + 1 < nt) { if (j + 2 < nt) ATT_WRITEK(a, 0); ATT_WRITEV(a, 1); }
;             ATT_BAR();
.Latt_it_e:
	ds_read_b128 v[6:9], v253 offset:17536
	ds_read_b128 v[10:13], v253 offset:17408
	ds_read_b128 v[14:17], v253 offset:21888
	ds_read_b128 v[18:21], v253 offset:21760
	ds_read_b128 v[22:25], v253 offset:26240
	ds_read_b128 v[26:29], v253 offset:26112
	ds_read_b128 v[30:33], v253 offset:30592
	ds_read_b128 v[34:37], v253 offset:30464
	v_exp_f32_e32 v152, v152
	v_exp_f32_e32 v153, v153
	v_exp_f32_e32 v154, v154
	v_exp_f32_e32 v155, v155
	v_exp_f32_e32 v156, v156
	v_exp_f32_e32 v157, v157
	v_exp_f32_e32 v158, v158
	v_exp_f32_e32 v159, v159
	v_exp_f32_e32 v168, v168
	v_exp_f32_e32 v169, v169
	v_exp_f32_e32 v170, v170
	v_exp_f32_e32 v171, v171
	v_exp_f32_e32 v172, v172
	v_exp_f32_e32 v173, v173
	v_exp_f32_e32 v174, v174
	v_exp_f32_e32 v175, v175
	v_cvt_pk_bf16_f32 v38, v152, v153
	v_cvt_pk_bf16_f32 v39, v154, v155
	v_cvt_pk_bf16_f32 v42, v156, v157
	v_cvt_pk_bf16_f32 v43, v158, v159
	v_pk_add_f32 v[234:235], v[234:235], v[152:153]
	v_pk_add_f32 v[234:235], v[234:235], v[154:155]
	v_pk_add_f32 v[236:237], v[236:237], v[156:157]
	v_pk_add_f32 v[236:237], v[236:237], v[158:159]
	v_cvt_pk_bf16_f32 v40, v168, v169
	v_cvt_pk_bf16_f32 v41, v170, v171
	v_cvt_pk_bf16_f32 v44, v172, v173
	v_cvt_pk_bf16_f32 v45, v174, v175
	v_pk_add_f32 v[234:235], v[234:235], v[168:169]
	v_pk_add_f32 v[234:235], v[234:235], v[170:171]
	v_pk_add_f32 v[236:237], v[236:237], v[172:173]
	v_pk_add_f32 v[236:237], v[236:237], v[174:175]
	s_waitcnt lgkmcnt(6)
	v_mfma_f32_16x16x32_bf16 v[64:67], v[6:9], v[112:115], v[48:51]
	ds_read_b128 v[6:9], v253 offset:17600
	v_exp_f32_e32 v192, v192
	v_exp_f32_e32 v193, v193
	v_mfma_f32_16x16x32_bf16 v[48:51], v[10:13], v[80:83], v[48:51]
	ds_read_b128 v[10:13], v253 offset:17472
	v_exp_f32_e32 v194, v194
	v_exp_f32_e32 v195, v195
	s_waitcnt lgkmcnt(6)
	v_mfma_f32_16x16x32_bf16 v[68:71], v[14:17], v[112:115], v[52:55]
	ds_read_b128 v[14:17], v253 offset:21952
	v_exp_f32_e32 v196, v196
	v_exp_f32_e32 v197, v197
	v_mfma_f32_16x16x32_bf16 v[52:55], v[18:21], v[80:83], v[52:55]
	ds_read_b128 v[18:21], v253 offset:21824
	v_exp_f32_e32 v198, v198
	v_exp_f32_e32 v199, v199
	s_waitcnt lgkmcnt(6)
	v_mfma_f32_16x16x32_bf16 v[72:75], v[22:25], v[112:115], v[56:59]
	ds_read_b128 v[22:25], v253 offset:26304
	v_exp_f32_e32 v200, v200
	v_exp_f32_e32 v201, v201
	v_mfma_f32_16x16x32_bf16 v[56:59], v[26:29], v[80:83], v[56:59]
	ds_read_b128 v[26:29], v253 offset:26176
	v_exp_f32_e32 v202, v202
	v_exp_f32_e32 v203, v203
	s_waitcnt lgkmcnt(6)
	v_mfma_f32_16x16x32_bf16 v[76:79], v[30:33], v[112:115], v[60:63]
	ds_read_b128 v[30:33], v253 offset:30656
	v_exp_f32_e32 v204, v204
	v_exp_f32_e32 v205, v205
	v_mfma_f32_16x16x32_bf16 v[60:63], v[34:37], v[80:83], v[60:63]
	ds_read_b128 v[34:37], v253 offset:30528
	v_exp_f32_e32 v206, v206
	v_exp_f32_e32 v207, v207
	s_waitcnt lgkmcnt(6)
	v_mfma_f32_16x16x32_bf16 v[64:67], v[6:9], v[128:131], v[64:67]
	ds_read_b128 v[6:9], v225 offset:0
	v_cvt_pk_bf16_f32 v0, v192, v193
	v_cvt_pk_bf16_f32 v1, v194, v195
	v_mfma_f32_16x16x32_bf16 v[48:51], v[10:13], v[104:107], v[48:51]
	ds_read_b128 v[10:13], v225 offset:2560
	v_cvt_pk_bf16_f32 v230, v196, v197
	v_cvt_pk_bf16_f32 v231, v198, v199
	s_waitcnt lgkmcnt(6)
	v_mfma_f32_16x16x32_bf16 v[68:71], v[14:17], v[128:131], v[68:71]
	ds_read_b128 v[14:17], v225 offset:5120
	v_pk_add_f32 v[234:235], v[234:235], v[192:193]
	v_pk_add_f32 v[234:235], v[234:235], v[194:195]
	v_mfma_f32_16x16x32_bf16 v[52:55], v[18:21], v[104:107], v[52:55]
	ds_read_b128 v[18:21], v225 offset:7680
	v_pk_add_f32 v[236:237], v[236:237], v[196:197]
	v_pk_add_f32 v[236:237], v[236:237], v[198:199]
	s_waitcnt lgkmcnt(6)
	v_mfma_f32_16x16x32_bf16 v[72:75], v[22:25], v[128:131], v[72:75]
	ds_read_b128 v[22:25], v225 offset:10240
	v_cvt_pk_bf16_f32 v2, v200, v201
	v_cvt_pk_bf16_f32 v3, v202, v203
	v_mfma_f32_16x16x32_bf16 v[56:59], v[26:29], v[104:107], v[56:59]
	ds_read_b128 v[26:29], v225 offset:12800
	v_cvt_pk_bf16_f32 v232, v204, v205
	v_cvt_pk_bf16_f32 v233, v206, v207
	s_waitcnt lgkmcnt(6)
	v_mfma_f32_16x16x32_bf16 v[76:79], v[30:33], v[128:131], v[76:79]
	ds_read_b128 v[30:33], v225 offset:15360
	v_pk_add_f32 v[234:235], v[234:235], v[200:201]
	v_pk_add_f32 v[234:235], v[234:235], v[202:203]
	v_mfma_f32_16x16x32_bf16 v[60:63], v[34:37], v[104:107], v[60:63]
	ds_read_b128 v[34:37], v225 offset:17920
	v_pk_add_f32 v[236:237], v[236:237], v[204:205]
	v_pk_add_f32 v[236:237], v[236:237], v[206:207]
	s_add_i32 s5, s4, 2
	s_cmp_le_u32 s5, s37
	s_cselect_b32 s45, s16, s18
	s_add_i32 s0, s37, 1
	s_cmp_le_u32 s5, s0
	s_cselect_b32 s43, s16, s18
	s_waitcnt lgkmcnt(6)
	v_mfma_f32_16x16x32_bf16 v[184:187], v[6:9], v[38:41], v[184:187]
	v_mov_b32_e32 v4, s43
	v_fma_f32 v152, |v47|, s19, v4
	v_subrev_f32_e32 v153, 0x3f800000, v47
	v_mfma_f32_16x16x32_bf16 v[188:191], v[6:9], v[42:45], v[188:191]
	ds_read_b128 v[6:9], v225 offset:64
	v_fma_f32 v153, |v153|, s19, v4
	v_subrev_f32_e32 v154, 0x40000000, v47
	v_fma_f32 v154, |v154|, s19, v4
	v_mfma_f32_16x16x32_bf16 v[180:183], v[10:13], v[38:41], v[180:183]
	v_subrev_f32_e32 v155, 0x40400000, v47
	v_fma_f32 v155, |v155|, s19, v4
	v_mfma_f32_16x16x32_bf16 v[176:179], v[10:13], v[42:45], v[176:179]
	ds_read_b128 v[10:13], v225 offset:2624
	v_mov_b32_e32 v4, s45
	v_subrev_f32_e32 v168, 0x41800000, v47
	s_waitcnt lgkmcnt(6)
	v_mfma_f32_16x16x32_bf16 v[164:167], v[14:17], v[38:41], v[164:167]
	v_fma_f32 v168, |v168|, s19, v4
	v_subrev_f32_e32 v169, 0x41880000, v47
	v_mfma_f32_16x16x32_bf16 v[160:163], v[14:17], v[42:45], v[160:163]
	ds_read_b128 v[14:17], v225 offset:5184
	v_fma_f32 v169, |v169|, s19, v4
	v_subrev_f32_e32 v170, 0x41900000, v47
	v_mfma_f32_16x16x32_bf16 v[148:151], v[18:21], v[38:41], v[148:151]
	v_fma_f32 v170, |v170|, s19, v4
	v_subrev_f32_e32 v171, 0x41980000, v47
	v_mfma_f32_16x16x32_bf16 v[144:147], v[18:21], v[42:45], v[144:147]
	ds_read_b128 v[18:21], v225 offset:7744
	v_fma_f32 v171, |v171|, s19, v4
	v_subrev_f32_e32 v192, 0x42000000, v47
	s_waitcnt lgkmcnt(6)
; #define LAS __attribute__((address_space(3)))
; #define ATT_LOADK(S, j) do { int pos_ = 64 * (j) + kr; pos_ = pos_ < LPOS ? pos_ : LPOS - 1; const bf16* kp_ = PK + (size_t)rowof(b, pos_) * 512 + hh * 128 + 8 * kseg; S##k0 = *(const u32x4*)kp_; S##k1 = *(const u32x4*)(kp_ + 64); } while (0)
; #define ATT_LOADV(S, j) do { const bf16* vp_ = Vt + ((size_t)bh * 128 + vr) * VT_LD + 64 * (j) + 8 * vseg; S##v0 = *(const u32x4*)vp_; S##v1 = *(const u32x4*)(vp_ + 32); } while (0)
; #define ATT_WRITEK(S, buf) do { LAS unsigned char* kb_ = lds + (buf) * KBUF + kr * KSTR + kseg * 16; *(LAS u32x4*)kb_ = S##k0; *(LAS u32x4*)(kb_ + 128) = S##k1; } while (0)
; #define ATT_WRITEV(S, buf) do { LAS unsigned char* vb_ = lds + VOFF + (buf) * VBUF + vr * VSTR + vseg * 16; *(LAS u32x4*)vb_ = S##v0; *(LAS u32x4*)(vb_ + 64) = S##v1; } while (0)
; #define ATT_BAR() do { asm volatile("s_waitcnt lgkmcnt(0)" ::: "memory"); __builtin_amdgcn_s_barrier(); asm volatile("" ::: "memory"); } while (0)
; __device__ __forceinline__ void att_pv(const LAS unsigned char* Vb, int nst, const f32x4 (&sc)[2][4], f32x4 (&O)[2][8], float& l0, float& l1, int fr, int fq) {
;     ...
;                 const LAS unsigned char* vp = Vb + (16 * dt + fr) * VSTR + (32 * ks2 + 4 * fq) * 2;
;                 const u32x2 va = *(const LAS u32x2*)vp, vb2 = *(const LAS u32x2*)(vp + 32);
;                 const bf16x8 vf = __builtin_bit_cast(bf16x8, (u32x4){va.x, va.y, vb2.x, vb2.y});
;                 O[0][dt] = __builtin_amdgcn_mfma_f32_16x16x32_bf16(vf, pf0, O[0][dt], 0, 0, 0);
;                 O[1][dt] = __builtin_amdgcn_mfma_f32_16x16x32_bf16(vf, pf1, O[1][dt], 0, 0, 0);
; __device__ __forceinline__ void attn_phase(const Params& P, LAS unsigned char* lds, int tid, int wid, int lane) {
;     ...
;             if (j + 1 < nt) { if (j + 2 < nt) ATT_WRITEK(a, 0); ATT_WRITEV(a, 1); }
;             ATT_BAR();
;             if (j + 1 >= nt) break;
;             if (j + 2 < nt) { if (j + 3 < nt) ATT_LOADK(a, j + 3); ATT_LOADV(a, j + 2); }
;             if (j + 2 < nt) att_qk(lds, qf, ATT_NST(j + 2), j + 2, qpos, slope2, fr, fq, scA);
;             att_pv(lds + VOFF + VBUF, ATT_NST(j + 1), scB, O, l0, l1, fr, fq);
;             if (j + 2 < nt) { if (j + 3 < nt) ATT_WRITEK(a, 1); ATT_WRITEV(a, 0); }
;             ATT_BAR();
	v_mfma_f32_16x16x32_bf16 v[140:143], v[22:25], v[38:41], v[140:143]
	v_fma_f32 v192, |v192|, s19, v4
	v_subrev_f32_e32 v193, 0x42040000, v47
	v_mfma_f32_16x16x32_bf16 v[136:139], v[22:25], v[42:45], v[136:139]
	ds_read_b128 v[22:25], v225 offset:10304
	v_fma_f32 v193, |v193|, s19, v4
	v_subrev_f32_e32 v194, 0x42080000, v47
	v_mfma_f32_16x16x32_bf16 v[132:135], v[26:29], v[38:41], v[132:135]
	v_fma_f32 v194, |v194|, s19, v4
	v_subrev_f32_e32 v195, 0x420c0000, v47
	v_mfma_f32_16x16x32_bf16 v[124:127], v[26:29], v[42:45], v[124:127]
	ds_read_b128 v[26:29], v225 offset:12864
	v_fma_f32 v195, |v195|, s19, v4
	v_subrev_f32_e32 v200, 0x42400000, v47
	s_waitcnt lgkmcnt(6)
	v_mfma_f32_16x16x32_bf16 v[120:123], v[30:33], v[38:41], v[120:123]
	v_fma_f32 v200, |v200|, s19, v4
	v_subrev_f32_e32 v201, 0x42440000, v47
	v_mfma_f32_16x16x32_bf16 v[116:119], v[30:33], v[42:45], v[116:119]
	ds_read_b128 v[30:33], v225 offset:15424
	v_fma_f32 v201, |v201|, s19, v4
	v_subrev_f32_e32 v202, 0x42480000, v47
	v_mfma_f32_16x16x32_bf16 v[108:111], v[34:37], v[38:41], v[108:111]
	v_fma_f32 v202, |v202|, s19, v4
	v_subrev_f32_e32 v203, 0x424c0000, v47
	v_mfma_f32_16x16x32_bf16 v[100:103], v[34:37], v[42:45], v[100:103]
	ds_read_b128 v[34:37], v225 offset:17984
	v_fma_f32 v203, |v203|, s19, v4
	v_add_f32_e32 v47, 0xc2800000, v47
	s_waitcnt vmcnt(0)
	ds_write_b128 v251, v[84:87] offset:0
	ds_write_b128 v251, v[88:91] offset:128
	ds_write2_b64 v247, v[92:93], v[94:95] offset1:2
	ds_write2_b64 v247, v[96:97], v[98:99] offset0:8 offset1:10
	s_sub_i32 s1, s36, 1
	s_add_i32 s0, s4, 3
	s_min_u32 s0, s0, s1
	s_add_i32 s5, s4, 2
	s_min_u32 s5, s5, s1
	s_lshl_b32 s0, s0, 6
	s_lshl_b32 s5, s5, 7
	v_add_u32_e32 v223, s0, v243
	v_min_u32_e32 v223, 0x7ff, v223
	v_lshl_add_u32 v223, v223, 10, v224
	s_add_u32 s26, s24, s5
	s_addc_u32 s27, s25, 0
	global_load_dwordx4 v[84:87], v223, s[22:23]
	global_load_dwordx4 v[88:91], v223, s[22:23] offset:128
	global_load_dwordx4 v[92:95], v46, s[26:27]
	global_load_dwordx4 v[96:99], v46, s[26:27] offset:64
	s_waitcnt lgkmcnt(10)
	v_mfma_f32_16x16x32_bf16 v[184:187], v[6:9], v[0:3], v[184:187]
	v_mfma_f32_16x16x32_bf16 v[188:191], v[6:9], v[230:233], v[188:191]
	v_mfma_f32_16x16x32_bf16 v[180:183], v[10:13], v[0:3], v[180:183]
	v_mfma_f32_16x16x32_bf16 v[176:179], v[10:13], v[230:233], v[176:179]
	s_waitcnt lgkmcnt(8)
	v_mfma_f32_16x16x32_bf16 v[164:167], v[14:17], v[0:3], v[164:167]
	v_mfma_f32_16x16x32_bf16 v[160:163], v[14:17], v[230:233], v[160:163]
	v_mfma_f32_16x16x32_bf16 v[148:151], v[18:21], v[0:3], v[148:151]
	v_mfma_f32_16x16x32_bf16 v[144:147], v[18:21], v[230:233], v[144:147]
	s_waitcnt lgkmcnt(6)
	v_mfma_f32_16x16x32_bf16 v[140:143], v[22:25], v[0:3], v[140:143]
	v_mfma_f32_16x16x32_bf16 v[136:139], v[22:25], v[230:233], v[136:139]
	v_mfma_f32_16x16x32_bf16 v[132:135], v[26:29], v[0:3], v[132:135]
	v_mfma_f32_16x16x32_bf16 v[124:127], v[26:29], v[230:233], v[124:127]
	s_waitcnt lgkmcnt(4)
	v_mfma_f32_16x16x32_bf16 v[120:123], v[30:33], v[0:3], v[120:123]
	v_mfma_f32_16x16x32_bf16 v[116:119], v[30:33], v[230:233], v[116:119]
	v_mfma_f32_16x16x32_bf16 v[108:111], v[34:37], v[0:3], v[108:111]
	v_mfma_f32_16x16x32_bf16 v[100:103], v[34:37], v[230:233], v[100:103]
	s_waitcnt lgkmcnt(0)
	s_barrier
	s_add_i32 s4, s4, 1
.Latt_it_o:
	ds_read_b128 v[6:9], v253 offset:128
	ds_read_b128 v[10:13], v253 offset:0
	ds_read_b128 v[14:17], v253 offset:4480
	ds_read_b128 v[18:21], v253 offset:4352
	ds_read_b128 v[22:25], v253 offset:8832
	ds_read_b128 v[26:29], v253 offset:8704
	ds_read_b128 v[30:33], v253 offset:13184
	ds_read_b128 v[34:37], v253 offset:13056
	v_exp_f32_e32 v48, v48
	v_exp_f32_e32 v49, v49
	v_exp_f32_e32 v50, v50
	v_exp_f32_e32 v51, v51
	v_exp_f32_e32 v64, v64
	v_exp_f32_e32 v65, v65
	v_exp_f32_e32 v66, v66
	v_exp_f32_e32 v67, v67
	v_exp_f32_e32 v52, v52
	v_exp_f32_e32 v53, v53
	v_exp_f32_e32 v54, v54
	v_exp_f32_e32 v55, v55
	v_exp_f32_e32 v68, v68
	v_exp_f32_e32 v69, v69
	v_exp_f32_e32 v70, v70
	v_exp_f32_e32 v71, v71
	v_cvt_pk_bf16_f32 v38, v48, v49
	v_cvt_pk_bf16_f32 v39, v50, v51
	v_cvt_pk_bf16_f32 v42, v64, v65
	v_cvt_pk_bf16_f32 v43, v66, v67
	v_pk_add_f32 v[234:235], v[234:235], v[48:49]
	v_pk_add_f32 v[234:235], v[234:235], v[50:51]
	v_pk_add_f32 v[236:237], v[236:237], v[64:65]
	v_pk_add_f32 v[236:237], v[236:237], v[66:67]
	v_cvt_pk_bf16_f32 v40, v52, v53
	v_cvt_pk_bf16_f32 v41, v54, v55
	v_cvt_pk_bf16_f32 v44, v68, v69
	v_cvt_pk_bf16_f32 v45, v70, v71
	v_pk_add_f32 v[234:235], v[234:235], v[52:53]
	v_pk_add_f32 v[234:235], v[234:235], v[54:55]
	v_pk_add_f32 v[236:237], v[236:237], v[68:69]
	v_pk_add_f32 v[236:237], v[236:237], v[70:71]
	s_waitcnt lgkmcnt(6)
	v_mfma_f32_16x16x32_bf16 v[156:159], v[6:9], v[112:115], v[152:155]
	ds_read_b128 v[6:9], v253 offset:192
	v_exp_f32_e32 v56, v56
	v_exp_f32_e32 v57, v57
	v_mfma_f32_16x16x32_bf16 v[152:155], v[10:13], v[80:83], v[152:155]
	ds_read_b128 v[10:13], v253 offset:64
	v_exp_f32_e32 v58, v58
	v_exp_f32_e32 v59, v59
	s_waitcnt lgkmcnt(6)
	v_mfma_f32_16x16x32_bf16 v[172:175], v[14:17], v[112:115], v[168:171]
	ds_read_b128 v[14:17], v253 offset:4544
	v_exp_f32_e32 v72, v72
	v_exp_f32_e32 v73, v73
	v_mfma_f32_16x16x32_bf16 v[168:171], v[18:21], v[80:83], v[168:171]
	ds_read_b128 v[18:21], v253 offset:4416
	v_exp_f32_e32 v74, v74
	v_exp_f32_e32 v75, v75
	s_waitcnt lgkmcnt(6)
	v_mfma_f32_16x16x32_bf16 v[196:199], v[22:25], v[112:115], v[192:195]
	ds_read_b128 v[22:25], v253 offset:8896
	v_exp_f32_e32 v60, v60
	v_exp_f32_e32 v61, v61
	v_mfma_f32_16x16x32_bf16 v[192:195], v[26:29], v[80:83], v[192:195]
	ds_read_b128 v[26:29], v253 offset:8768
	v_exp_f32_e32 v62, v62
	v_exp_f32_e32 v63, v63
	s_waitcnt lgkmcnt(6)
; #define LAS __attribute__((address_space(3)))
; __device__ __forceinline__ void att_pv(const LAS unsigned char* Vb, int nst, const f32x4 (&sc)[2][4], f32x4 (&O)[2][8], float& l0, float& l1, int fr, int fq) {
;     constexpr int VSTR = 144;
;     if (nst <= 0) return;
;     unsigned pw[2][4][2];
; #pragma unroll
;     for (int st = 0; st < 4; ++st) {
;         if (st < nst) {
;             float p0[4], p1[4];
; #pragma unroll
;             for (int e = 0; e < 4; ++e) { p0[e] = __builtin_amdgcn_exp2f(sc[0][st][e]); p1[e] = __builtin_amdgcn_exp2f(sc[1][st][e]); l0 += p0[e]; l1 += p1[e]; }
;             pw[0][st][0] = pk2(p0[0], p0[1]); pw[0][st][1] = pk2(p0[2], p0[3]); pw[1][st][0] = pk2(p1[0], p1[1]); pw[1][st][1] = pk2(p1[2], p1[3]);
;         } else { pw[0][st][0] = 0u; pw[0][st][1] = 0u; pw[1][st][0] = 0u; pw[1][st][1] = 0u; }
;     }
; #pragma unroll
;     for (int ks2 = 0; ks2 < 2; ++ks2) {
;         if (ks2 == 0 || nst == 4) {
;             const u32x4 a0 = (u32x4){pw[0][2 * ks2][0], pw[0][2 * ks2][1], pw[0][2 * ks2 + 1][0], pw[0][2 * ks2 + 1][1]};
;             const u32x4 a1 = (u32x4){pw[1][2 * ks2][0], pw[1][2 * ks2][1], pw[1][2 * ks2 + 1][0], pw[1][2 * ks2 + 1][1]};
;             const bf16x8 pf0 = __builtin_bit_cast(bf16x8, a0), pf1 = __builtin_bit_cast(bf16x8, a1);
; #pragma unroll
;             for (int dt = 0; dt < 8; ++dt) {
;                 const LAS unsigned char* vp = Vb + (16 * dt + fr) * VSTR + (32 * ks2 + 4 * fq) * 2;
;                 const u32x2 va = *(const LAS u32x2*)vp, vb2 = *(const LAS u32x2*)(vp + 32);
;                 const bf16x8 vf = __builtin_bit_cast(bf16x8, (u32x4){va.x, va.y, vb2.x, vb2.y});
;                 O[0][dt] = __builtin_amdgcn_mfma_f32_16x16x32_bf16(vf, pf0, O[0][dt], 0, 0, 0);
;                 O[1][dt] = __builtin_amdgcn_mfma_f32_16x16x32_bf16(vf, pf1, O[1][dt], 0, 0, 0);
;             }
;         }
;     }
; __device__ __forceinline__ void attn_phase(const Params& P, LAS unsigned char* lds, int tid, int wid, int lane) {
;     ...
;             if (j + 2 < nt) { if (j + 3 < nt) ATT_LOADK(a, j + 3); ATT_LOADV(a, j + 2); }
;             if (j + 2 < nt) att_qk(lds, qf, ATT_NST(j + 2), j + 2, qpos, slope2, fr, fq, scA);
;             att_pv(lds + VOFF + VBUF, ATT_NST(j + 1), scB, O, l0, l1, fr, fq);
;             if (j + 2 < nt) { if (j + 3 < nt) ATT_WRITEK(a, 1); ATT_WRITEV(a, 0); }
;             ATT_BAR();
	v_mfma_f32_16x16x32_bf16 v[204:207], v[30:33], v[112:115], v[200:203]
	ds_read_b128 v[30:33], v253 offset:13248
	v_exp_f32_e32 v76, v76
	v_exp_f32_e32 v77, v77
	v_mfma_f32_16x16x32_bf16 v[200:203], v[34:37], v[80:83], v[200:203]
	ds_read_b128 v[34:37], v253 offset:13120
	v_exp_f32_e32 v78, v78
	v_exp_f32_e32 v79, v79
	s_waitcnt lgkmcnt(6)
	v_mfma_f32_16x16x32_bf16 v[156:159], v[6:9], v[128:131], v[156:159]
	ds_read_b128 v[6:9], v246 offset:0
	v_cvt_pk_bf16_f32 v0, v56, v57
	v_cvt_pk_bf16_f32 v1, v58, v59
	v_mfma_f32_16x16x32_bf16 v[152:155], v[10:13], v[104:107], v[152:155]
	ds_read_b128 v[10:13], v246 offset:2560
	v_cvt_pk_bf16_f32 v230, v72, v73
	v_cvt_pk_bf16_f32 v231, v74, v75
	s_waitcnt lgkmcnt(6)
	v_mfma_f32_16x16x32_bf16 v[172:175], v[14:17], v[128:131], v[172:175]
	ds_read_b128 v[14:17], v246 offset:5120
	v_pk_add_f32 v[234:235], v[234:235], v[56:57]
	v_pk_add_f32 v[234:235], v[234:235], v[58:59]
	v_mfma_f32_16x16x32_bf16 v[168:171], v[18:21], v[104:107], v[168:171]
	ds_read_b128 v[18:21], v246 offset:7680
	v_pk_add_f32 v[236:237], v[236:237], v[72:73]
	v_pk_add_f32 v[236:237], v[236:237], v[74:75]
	s_waitcnt lgkmcnt(6)
	v_mfma_f32_16x16x32_bf16 v[196:199], v[22:25], v[128:131], v[196:199]
	ds_read_b128 v[22:25], v246 offset:10240
	v_cvt_pk_bf16_f32 v2, v60, v61
	v_cvt_pk_bf16_f32 v3, v62, v63
	v_mfma_f32_16x16x32_bf16 v[192:195], v[26:29], v[104:107], v[192:195]
	ds_read_b128 v[26:29], v246 offset:12800
	v_cvt_pk_bf16_f32 v232, v76, v77
	v_cvt_pk_bf16_f32 v233, v78, v79
	s_waitcnt lgkmcnt(6)
	v_mfma_f32_16x16x32_bf16 v[204:207], v[30:33], v[128:131], v[204:207]
	ds_read_b128 v[30:33], v246 offset:15360
	v_pk_add_f32 v[234:235], v[234:235], v[60:61]
	v_pk_add_f32 v[234:235], v[234:235], v[62:63]
	v_mfma_f32_16x16x32_bf16 v[200:203], v[34:37], v[104:107], v[200:203]
	ds_read_b128 v[34:37], v246 offset:17920
	v_pk_add_f32 v[236:237], v[236:237], v[76:77]
	v_pk_add_f32 v[236:237], v[236:237], v[78:79]
	s_add_i32 s5, s4, 2
	s_cmp_le_u32 s5, s37
	s_cselect_b32 s45, s16, s18
	s_add_i32 s0, s37, 1
	s_cmp_le_u32 s5, s0
	s_cselect_b32 s43, s16, s18
	s_waitcnt lgkmcnt(6)
	v_mfma_f32_16x16x32_bf16 v[184:187], v[6:9], v[38:41], v[184:187]
	v_mov_b32_e32 v4, s43
	v_fma_f32 v48, |v47|, s19, v4
	v_subrev_f32_e32 v49, 0x3f800000, v47
	v_mfma_f32_16x16x32_bf16 v[188:191], v[6:9], v[42:45], v[188:191]
	ds_read_b128 v[6:9], v246 offset:64
	v_fma_f32 v49, |v49|, s19, v4
	v_subrev_f32_e32 v50, 0x40000000, v47
	v_fma_f32 v50, |v50|, s19, v4
	v_mfma_f32_16x16x32_bf16 v[180:183], v[10:13], v[38:41], v[180:183]
	v_subrev_f32_e32 v51, 0x40400000, v47
	v_fma_f32 v51, |v51|, s19, v4
	v_mfma_f32_16x16x32_bf16 v[176:179], v[10:13], v[42:45], v[176:179]
	ds_read_b128 v[10:13], v246 offset:2624
	v_mov_b32_e32 v4, s45
	v_subrev_f32_e32 v52, 0x41800000, v47
	s_waitcnt lgkmcnt(6)
	v_mfma_f32_16x16x32_bf16 v[164:167], v[14:17], v[38:41], v[164:167]
	v_fma_f32 v52, |v52|, s19, v4
	v_subrev_f32_e32 v53, 0x41880000, v47
	v_mfma_f32_16x16x32_bf16 v[160:163], v[14:17], v[42:45], v[160:163]
	ds_read_b128 v[14:17], v246 offset:5184
	v_fma_f32 v53, |v53|, s19, v4
	v_subrev_f32_e32 v54, 0x41900000, v47
	v_mfma_f32_16x16x32_bf16 v[148:151], v[18:21], v[38:41], v[148:151]
	v_fma_f32 v54, |v54|, s19, v4
	v_subrev_f32_e32 v55, 0x41980000, v47
	v_mfma_f32_16x16x32_bf16 v[144:147], v[18:21], v[42:45], v[144:147]
	ds_read_b128 v[18:21], v246 offset:7744
	v_fma_f32 v55, |v55|, s19, v4
	v_subrev_f32_e32 v56, 0x42000000, v47
	s_waitcnt lgkmcnt(6)
	v_mfma_f32_16x16x32_bf16 v[140:143], v[22:25], v[38:41], v[140:143]
	v_fma_f32 v56, |v56|, s19, v4
	v_subrev_f32_e32 v57, 0x42040000, v47
	v_mfma_f32_16x16x32_bf16 v[136:139], v[22:25], v[42:45], v[136:139]
	ds_read_b128 v[22:25], v246 offset:10304
	v_fma_f32 v57, |v57|, s19, v4
	v_subrev_f32_e32 v58, 0x42080000, v47
	v_mfma_f32_16x16x32_bf16 v[132:135], v[26:29], v[38:41], v[132:135]
	v_fma_f32 v58, |v58|, s19, v4
	v_subrev_f32_e32 v59, 0x420c0000, v47
	v_mfma_f32_16x16x32_bf16 v[124:127], v[26:29], v[42:45], v[124:127]
	ds_read_b128 v[26:29], v246 offset:12864
	v_fma_f32 v59, |v59|, s19, v4
	v_subrev_f32_e32 v60, 0x42400000, v47
	s_waitcnt lgkmcnt(6)
	v_mfma_f32_16x16x32_bf16 v[120:123], v[30:33], v[38:41], v[120:123]
	v_fma_f32 v60, |v60|, s19, v4
	v_subrev_f32_e32 v61, 0x42440000, v47
	v_mfma_f32_16x16x32_bf16 v[116:119], v[30:33], v[42:45], v[116:119]
	ds_read_b128 v[30:33], v246 offset:15424
	v_fma_f32 v61, |v61|, s19, v4
	v_subrev_f32_e32 v62, 0x42480000, v47
	v_mfma_f32_16x16x32_bf16 v[108:111], v[34:37], v[38:41], v[108:111]
	v_fma_f32 v62, |v62|, s19, v4
	v_subrev_f32_e32 v63, 0x424c0000, v47
	v_mfma_f32_16x16x32_bf16 v[100:103], v[34:37], v[42:45], v[100:103]
	ds_read_b128 v[34:37], v246 offset:17984
	v_fma_f32 v63, |v63|, s19, v4
	v_add_f32_e32 v47, 0xc2800000, v47
	s_waitcnt vmcnt(0)
	ds_write_b128 v251, v[84:87] offset:17408
	ds_write_b128 v251, v[88:91] offset:17536
	ds_write2_b64 v252, v[92:93], v[94:95] offset1:2
	ds_write2_b64 v252, v[96:97], v[98:99] offset0:8 offset1:10
	s_sub_i32 s1, s36, 1
	s_add_i32 s0, s4, 3
	s_min_u32 s0, s0, s1
	s_add_i32 s5, s4, 2
	s_min_u32 s5, s5, s1
	s_lshl_b32 s0, s0, 6
	s_lshl_b32 s5, s5, 7
	v_add_u32_e32 v223, s0, v243
	v_min_u32_e32 v223, 0x7ff, v223
	v_lshl_add_u32 v223, v223, 10, v224
	s_add_u32 s26, s24, s5
	s_addc_u32 s27, s25, 0
	global_load_dwordx4 v[84:87], v223, s[22:23]
	global_load_dwordx4 v[88:91], v223, s[22:23] offset:128
	global_load_dwordx4 v[92:95], v46, s[26:27]
	global_load_dwordx4 v[96:99], v46, s[26:27] offset:64
	s_waitcnt lgkmcnt(10)
	v_mfma_f32_16x16x32_bf16 v[184:187], v[6:9], v[0:3], v[184:187]
	v_mfma_f32_16x16x32_bf16 v[188:191], v[6:9], v[230:233], v[188:191]
	v_mfma_f32_16x16x32_bf16 v[180:183], v[10:13], v[0:3], v[180:183]
	v_mfma_f32_16x16x32_bf16 v[176:179], v[10:13], v[230:233], v[176:179]
	s_waitcnt lgkmcnt(8)
	v_mfma_f32_16x16x32_bf16 v[164:167], v[14:17], v[0:3], v[164:167]
	v_mfma_f32_16x16x32_bf16 v[160:163], v[14:17], v[230:233], v[160:163]
	v_mfma_f32_16x16x32_bf16 v[148:151], v[18:21], v[0:3], v[148:151]
	v_mfma_f32_16x16x32_bf16 v[144:147], v[18:21], v[230:233], v[144:147]
	s_waitcnt lgkmcnt(6)
	v_mfma_f32_16x16x32_bf16 v[140:143], v[22:25], v[0:3], v[140:143]
	v_mfma_f32_16x16x32_bf16 v[136:139], v[22:25], v[230:233], v[136:139]
	v_mfma_f32_16x16x32_bf16 v[132:135], v[26:29], v[0:3], v[132:135]
	v_mfma_f32_16x16x32_bf16 v[124:127], v[26:29], v[230:233], v[124:127]
	s_waitcnt lgkmcnt(4)
	v_mfma_f32_16x16x32_bf16 v[120:123], v[30:33], v[0:3], v[120:123]
	v_mfma_f32_16x16x32_bf16 v[116:119], v[30:33], v[230:233], v[116:119]
	v_mfma_f32_16x16x32_bf16 v[108:111], v[34:37], v[0:3], v[108:111]
	v_mfma_f32_16x16x32_bf16 v[100:103], v[34:37], v[230:233], v[100:103]
	s_waitcnt lgkmcnt(0)
	s_barrier
	s_add_i32 s4, s4, 1
	s_branch .Latt_top
; #define LAS __attribute__((address_space(3)))
; __device__ __forceinline__ unsigned pk2(float lo, float hi) { return pg8::cvt_pk_bf16(lo, hi); }
; __device__ __forceinline__ void att_pv(const LAS unsigned char* Vb, int nst, const f32x4 (&sc)[2][4], f32x4 (&O)[2][8], float& l0, float& l1, int fr, int fq) {
;     constexpr int VSTR = 144;
;     if (nst <= 0) return;
;     unsigned pw[2][4][2];
; #pragma unroll
;     for (int st = 0; st < 4; ++st) {
;         if (st < nst) {
;             float p0[4], p1[4];
; #pragma unroll
;             for (int e = 0; e < 4; ++e) { p0[e] = __builtin_amdgcn_exp2f(sc[0][st][e]); p1[e] = __builtin_amdgcn_exp2f(sc[1][st][e]); l0 += p0[e]; l1 += p1[e]; }
;             pw[0][st][0] = pk2(p0[0], p0[1]); pw[0][st][1] = pk2(p0[2], p0[3]); pw[1][st][0] = pk2(p1[0], p1[1]); pw[1][st][1] = pk2(p1[2], p1[3]);
;         } else { pw[0][st][0] = 0u; pw[0][st][1] = 0u; pw[1][st][0] = 0u; pw[1][st][1] = 0u; }
;     }
; #pragma unroll
;     for (int ks2 = 0; ks2 < 2; ++ks2) {
;         if (ks2 == 0 || nst == 4) {
;             const u32x4 a0 = (u32x4){pw[0][2 * ks2][0], pw[0][2 * ks2][1], pw[0][2 * ks2 + 1][0], pw[0][2 * ks2 + 1][1]};
;             const u32x4 a1 = (u32x4){pw[1][2 * ks2][0], pw[1][2 * ks2][1], pw[1][2 * ks2 + 1][0], pw[1][2 * ks2 + 1][1]};
;             const bf16x8 pf0 = __builtin_bit_cast(bf16x8, a0), pf1 = __builtin_bit_cast(bf16x8, a1);
; #pragma unroll
;             for (int dt = 0; dt < 8; ++dt) {
;                 const LAS unsigned char* vp = Vb + (16 * dt + fr) * VSTR + (32 * ks2 + 4 * fq) * 2;
;                 const u32x2 va = *(const LAS u32x2*)vp, vb2 = *(const LAS u32x2*)(vp + 32);
;                 const bf16x8 vf = __builtin_bit_cast(bf16x8, (u32x4){va.x, va.y, vb2.x, vb2.y});
;                 O[0][dt] = __builtin_amdgcn_mfma_f32_16x16x32_bf16(vf, pf0, O[0][dt], 0, 0, 0);
;                 O[1][dt] = __builtin_amdgcn_mfma_f32_16x16x32_bf16(vf, pf1, O[1][dt], 0, 0, 0);
;             }
;         }
;     }
.Latt_it_l:
	ds_read_b128 v[6:9], v225 offset:0
	ds_read_b128 v[10:13], v225 offset:2560
	ds_read_b128 v[14:17], v225 offset:5120
	ds_read_b128 v[18:21], v225 offset:7680
	ds_read_b128 v[22:25], v225 offset:10240
	ds_read_b128 v[26:29], v225 offset:12800
	ds_read_b128 v[30:33], v225 offset:15360
	ds_read_b128 v[34:37], v225 offset:17920
	v_exp_f32_e32 v152, v152
	v_exp_f32_e32 v153, v153
	v_exp_f32_e32 v154, v154
	v_exp_f32_e32 v155, v155
	v_exp_f32_e32 v156, v156
	v_exp_f32_e32 v157, v157
	v_exp_f32_e32 v158, v158
	v_exp_f32_e32 v159, v159
	v_exp_f32_e32 v168, v168
	v_exp_f32_e32 v169, v169
	v_exp_f32_e32 v170, v170
	v_exp_f32_e32 v171, v171
	v_exp_f32_e32 v172, v172
	v_exp_f32_e32 v173, v173
	v_exp_f32_e32 v174, v174
	v_exp_f32_e32 v175, v175
	v_cvt_pk_bf16_f32 v38, v152, v153
	v_cvt_pk_bf16_f32 v39, v154, v155
	v_cvt_pk_bf16_f32 v42, v156, v157
	v_cvt_pk_bf16_f32 v43, v158, v159
	v_pk_add_f32 v[234:235], v[234:235], v[152:153]
	v_pk_add_f32 v[234:235], v[234:235], v[154:155]
	v_pk_add_f32 v[236:237], v[236:237], v[156:157]
	v_pk_add_f32 v[236:237], v[236:237], v[158:159]
	v_cvt_pk_bf16_f32 v40, v168, v169
	v_cvt_pk_bf16_f32 v41, v170, v171
	v_cvt_pk_bf16_f32 v44, v172, v173
	v_cvt_pk_bf16_f32 v45, v174, v175
	v_pk_add_f32 v[234:235], v[234:235], v[168:169]
	v_pk_add_f32 v[234:235], v[234:235], v[170:171]
	v_pk_add_f32 v[236:237], v[236:237], v[172:173]
	v_pk_add_f32 v[236:237], v[236:237], v[174:175]
	s_waitcnt lgkmcnt(6)
	v_mfma_f32_16x16x32_bf16 v[184:187], v[6:9], v[38:41], v[184:187]
	v_exp_f32_e32 v192, v192
	v_exp_f32_e32 v193, v193
	v_mfma_f32_16x16x32_bf16 v[188:191], v[6:9], v[42:45], v[188:191]
	ds_read_b128 v[6:9], v225 offset:64
	v_exp_f32_e32 v194, v194
	v_exp_f32_e32 v195, v195
	v_mfma_f32_16x16x32_bf16 v[180:183], v[10:13], v[38:41], v[180:183]
	v_exp_f32_e32 v196, v196
	v_exp_f32_e32 v197, v197
	v_mfma_f32_16x16x32_bf16 v[176:179], v[10:13], v[42:45], v[176:179]
	ds_read_b128 v[10:13], v225 offset:2624
	v_exp_f32_e32 v198, v198
	v_exp_f32_e32 v199, v199
	s_waitcnt lgkmcnt(6)
	v_mfma_f32_16x16x32_bf16 v[164:167], v[14:17], v[38:41], v[164:167]
	v_exp_f32_e32 v200, v200
	v_exp_f32_e32 v201, v201
	v_mfma_f32_16x16x32_bf16 v[160:163], v[14:17], v[42:45], v[160:163]
	ds_read_b128 v[14:17], v225 offset:5184
	v_exp_f32_e32 v202, v202
	v_exp_f32_e32 v203, v203
	v_mfma_f32_16x16x32_bf16 v[148:151], v[18:21], v[38:41], v[148:151]
	v_exp_f32_e32 v204, v204
	v_exp_f32_e32 v205, v205
	v_mfma_f32_16x16x32_bf16 v[144:147], v[18:21], v[42:45], v[144:147]
	ds_read_b128 v[18:21], v225 offset:7744
	v_exp_f32_e32 v206, v206
	v_exp_f32_e32 v207, v207
	s_waitcnt lgkmcnt(6)
	v_mfma_f32_16x16x32_bf16 v[140:143], v[22:25], v[38:41], v[140:143]
	v_cvt_pk_bf16_f32 v0, v192, v193
	v_cvt_pk_bf16_f32 v1, v194, v195
	v_mfma_f32_16x16x32_bf16 v[136:139], v[22:25], v[42:45], v[136:139]
	ds_read_b128 v[22:25], v225 offset:10304
	v_cvt_pk_bf16_f32 v230, v196, v197
	v_cvt_pk_bf16_f32 v231, v198, v199
	v_mfma_f32_16x16x32_bf16 v[132:135], v[26:29], v[38:41], v[132:135]
	v_pk_add_f32 v[234:235], v[234:235], v[192:193]
	v_pk_add_f32 v[234:235], v[234:235], v[194:195]
	v_mfma_f32_16x16x32_bf16 v[124:127], v[26:29], v[42:45], v[124:127]
	ds_read_b128 v[26:29], v225 offset:12864
	v_pk_add_f32 v[236:237], v[236:237], v[196:197]
	v_pk_add_f32 v[236:237], v[236:237], v[198:199]
	s_waitcnt lgkmcnt(6)
	v_mfma_f32_16x16x32_bf16 v[120:123], v[30:33], v[38:41], v[120:123]
	v_cvt_pk_bf16_f32 v2, v200, v201
	v_cvt_pk_bf16_f32 v3, v202, v203
	v_mfma_f32_16x16x32_bf16 v[116:119], v[30:33], v[42:45], v[116:119]
	ds_read_b128 v[30:33], v225 offset:15424
	v_cvt_pk_bf16_f32 v232, v204, v205
	v_cvt_pk_bf16_f32 v233, v206, v207
	v_mfma_f32_16x16x32_bf16 v[108:111], v[34:37], v[38:41], v[108:111]
	v_pk_add_f32 v[234:235], v[234:235], v[200:201]
	v_pk_add_f32 v[234:235], v[234:235], v[202:203]
	v_mfma_f32_16x16x32_bf16 v[100:103], v[34:37], v[42:45], v[100:103]
	ds_read_b128 v[34:37], v225 offset:17984
	v_pk_add_f32 v[236:237], v[236:237], v[204:205]
	v_pk_add_f32 v[236:237], v[236:237], v[206:207]
	s_waitcnt lgkmcnt(6)
	v_mfma_f32_16x16x32_bf16 v[184:187], v[6:9], v[0:3], v[184:187]
	v_mfma_f32_16x16x32_bf16 v[188:191], v[6:9], v[230:233], v[188:191]
	v_mfma_f32_16x16x32_bf16 v[180:183], v[10:13], v[0:3], v[180:183]
	v_mfma_f32_16x16x32_bf16 v[176:179], v[10:13], v[230:233], v[176:179]
	s_waitcnt lgkmcnt(4)
	v_mfma_f32_16x16x32_bf16 v[164:167], v[14:17], v[0:3], v[164:167]
	v_mfma_f32_16x16x32_bf16 v[160:163], v[14:17], v[230:233], v[160:163]
	v_mfma_f32_16x16x32_bf16 v[148:151], v[18:21], v[0:3], v[148:151]
	v_mfma_f32_16x16x32_bf16 v[144:147], v[18:21], v[230:233], v[144:147]
	s_waitcnt lgkmcnt(2)
	v_mfma_f32_16x16x32_bf16 v[140:143], v[22:25], v[0:3], v[140:143]
	v_mfma_f32_16x16x32_bf16 v[136:139], v[22:25], v[230:233], v[136:139]
	v_mfma_f32_16x16x32_bf16 v[132:135], v[26:29], v[0:3], v[132:135]
	v_mfma_f32_16x16x32_bf16 v[124:127], v[26:29], v[230:233], v[124:127]
	s_waitcnt lgkmcnt(0)
	v_mfma_f32_16x16x32_bf16 v[120:123], v[30:33], v[0:3], v[120:123]
	v_mfma_f32_16x16x32_bf16 v[116:119], v[30:33], v[230:233], v[116:119]
	v_mfma_f32_16x16x32_bf16 v[108:111], v[34:37], v[0:3], v[108:111]
	v_mfma_f32_16x16x32_bf16 v[100:103], v[34:37], v[230:233], v[100:103]
